# v19 plus top-k radix-select steps precomputing both next trials (one fewer dependent SALU op per step)
# baseline (speedup 1.0000x reference)
; DI void nsa_block(const bf16_t* P1, const bf16_t* VT1, const bf16_t* KSF, const bf16_t* KC, const bf16_t* VCT, bf16_t* O, const unsigned* kmx, int b, int g, int t0b, int wave, int lane, unsigned char* lds) {
;     ...
;     for (int k2 = 0; k2 < 8; ++k2) {
;         const int cur = (t0w + k2) >> 6;
;         unsigned long long ma, mb;
;         if (cur < 16) { ma = __ballot(lane <= cur); mb = 0ull; }
;         else {
;             const float va = impA[k2 * 128 + lane] + impB[k2 * 128 + lane], vb = impA[k2 * 128 + 64 + lane] + impB[k2 * 128 + 64 + lane];
;             const int sa = lane, sb = lane + 64;
;             const unsigned ka = (sa >= 1 && sa <= cur - 2) ? __float_as_uint(va) + 1u : 0u, kb = (sb <= cur - 2) ? __float_as_uint(vb) + 1u : 0u;
;             unsigned tau = 0u;
;     ...
;                 const int cnt = __popcll(__ballot(ka >= trial)) + __popcll(__ballot(kb >= trial)); if (cnt >= 13) tau = trial; }
.LBB0_1019:
	s_movk_i32 s0, 0x3ff
	v_lshrrev_b32_e32 v38, 6, v36
	v_cmp_lt_u32_e32 vcc, s0, v36
	s_and_saveexec_b64 s[0:1], vcc
	s_xor_b64 s[2:3], exec, s[0:1]
	s_cbranch_execz .LBB0_1027
	ds_read2st64_b32 v[32:33], v37 offset1:1
	s_waitcnt lgkmcnt(1)
	ds_read2st64_b32 v[34:35], v37 offset0:16 offset1:17
	s_mov_b64 s[18:19], -1
	s_waitcnt lgkmcnt(0)
	v_add_f32_e32 v32, v32, v34
	v_add_u32_e32 v34, -2, v38
	v_cmp_gt_i32_e32 vcc, v176, v34
	v_add_f32_e32 v33, v33, v35
	s_or_b64 s[0:1], s[4:5], vcc
	v_add_u32_e32 v32, 1, v32
	v_cndmask_b32_e64 v32, v32, 0, s[0:1]
	v_add_u32_e32 v33, 1, v33
	v_cmp_le_i32_e32 vcc, v172, v34
	s_nop 1
	v_cndmask_b32_e32 v33, 0, v33, vcc
	v_cmp_gt_i32_e32 vcc, 0, v32
	s_bcnt1_i32_b64 s0, vcc
	v_cmp_gt_i32_e32 vcc, 0, v33
	s_bcnt1_i32_b64 s1, vcc
	s_add_i32 s1, s1, s0
	s_cmp_gt_u32 s1, 12
	s_cselect_b32 s0, 0x80000000, 0
	s_or_b32 s1, s0, 2.0
	v_cmp_le_u32_e64 s[12:13], s1, v32
	v_cmp_le_u32_e32 vcc, s1, v33
	s_or_b32 s14, s1, 0x20000000
	s_or_b32 s15, s0, 0x20000000
	s_bcnt1_i32_b64 s10, s[12:13]
	s_bcnt1_i32_b64 s11, vcc
	s_add_i32 s11, s11, s10
	s_cmp_gt_u32 s11, 12
	s_cselect_b32 s0, s1, s0
	s_cselect_b32 s1, s14, s15
	v_cmp_le_u32_e64 s[12:13], s1, v32
	v_cmp_le_u32_e32 vcc, s1, v33
	s_or_b32 s14, s1, 0x10000000
	s_or_b32 s15, s0, 0x10000000
	s_bcnt1_i32_b64 s10, s[12:13]
	s_bcnt1_i32_b64 s11, vcc
	s_add_i32 s11, s11, s10
	s_cmp_gt_u32 s11, 12
	s_cselect_b32 s0, s1, s0
	s_cselect_b32 s1, s14, s15
	v_cmp_le_u32_e64 s[12:13], s1, v32
	v_cmp_le_u32_e32 vcc, s1, v33
	s_or_b32 s14, s1, 0x8000000
	s_or_b32 s15, s0, 0x8000000
	s_bcnt1_i32_b64 s10, s[12:13]
	s_bcnt1_i32_b64 s11, vcc
	s_add_i32 s11, s11, s10
	s_cmp_gt_u32 s11, 12
	s_cselect_b32 s0, s1, s0
	s_cselect_b32 s1, s14, s15
	v_cmp_le_u32_e64 s[12:13], s1, v32
	v_cmp_le_u32_e32 vcc, s1, v33
	s_or_b32 s14, s1, 0x4000000
	s_or_b32 s15, s0, 0x4000000
	s_bcnt1_i32_b64 s10, s[12:13]
	s_bcnt1_i32_b64 s11, vcc
	s_add_i32 s11, s11, s10
	s_cmp_gt_u32 s11, 12
	s_cselect_b32 s0, s1, s0
	s_cselect_b32 s1, s14, s15
	v_cmp_le_u32_e64 s[12:13], s1, v32
	v_cmp_le_u32_e32 vcc, s1, v33
	s_or_b32 s14, s1, 0x2000000
	s_or_b32 s15, s0, 0x2000000
	s_bcnt1_i32_b64 s10, s[12:13]
	s_bcnt1_i32_b64 s11, vcc
	s_add_i32 s11, s11, s10
	s_cmp_gt_u32 s11, 12
	s_cselect_b32 s0, s1, s0
	s_cselect_b32 s1, s14, s15
	v_cmp_le_u32_e64 s[12:13], s1, v32
	v_cmp_le_u32_e32 vcc, s1, v33
	s_or_b32 s14, s1, 0x1000000
	s_or_b32 s15, s0, 0x1000000
	s_bcnt1_i32_b64 s10, s[12:13]
	s_bcnt1_i32_b64 s11, vcc
	s_add_i32 s11, s11, s10
	s_cmp_gt_u32 s11, 12
	s_cselect_b32 s0, s1, s0
	s_cselect_b32 s1, s14, s15
	v_cmp_le_u32_e64 s[12:13], s1, v32
	v_cmp_le_u32_e32 vcc, s1, v33
	s_or_b32 s14, s1, 0x800000
	s_or_b32 s15, s0, 0x800000
	s_bcnt1_i32_b64 s10, s[12:13]
	s_bcnt1_i32_b64 s11, vcc
	s_add_i32 s11, s11, s10
	s_cmp_gt_u32 s11, 12
	s_cselect_b32 s0, s1, s0
	s_cselect_b32 s1, s14, s15
	v_cmp_le_u32_e64 s[12:13], s1, v32
	v_cmp_le_u32_e32 vcc, s1, v33
	s_or_b32 s14, s1, 0x400000
	s_or_b32 s15, s0, 0x400000
	s_bcnt1_i32_b64 s10, s[12:13]
	s_bcnt1_i32_b64 s11, vcc
	s_add_i32 s11, s11, s10
	s_cmp_gt_u32 s11, 12
	s_cselect_b32 s0, s1, s0
	s_cselect_b32 s1, s14, s15
	v_cmp_le_u32_e64 s[12:13], s1, v32
	v_cmp_le_u32_e32 vcc, s1, v33
	s_or_b32 s14, s1, 0x200000
	s_or_b32 s15, s0, 0x200000
	s_bcnt1_i32_b64 s10, s[12:13]
	s_bcnt1_i32_b64 s11, vcc
	s_add_i32 s11, s11, s10
	s_cmp_gt_u32 s11, 12
	s_cselect_b32 s0, s1, s0
	s_cselect_b32 s1, s14, s15
	v_cmp_le_u32_e64 s[12:13], s1, v32
	v_cmp_le_u32_e32 vcc, s1, v33
	s_or_b32 s14, s1, 0x100000
	s_or_b32 s15, s0, 0x100000
	s_bcnt1_i32_b64 s10, s[12:13]
	s_bcnt1_i32_b64 s11, vcc
	s_add_i32 s11, s11, s10
	s_cmp_gt_u32 s11, 12
	s_cselect_b32 s0, s1, s0
	s_cselect_b32 s1, s14, s15
	v_cmp_le_u32_e64 s[12:13], s1, v32
	v_cmp_le_u32_e32 vcc, s1, v33
	s_or_b32 s14, s1, 0x80000
	s_or_b32 s15, s0, 0x80000
	s_bcnt1_i32_b64 s10, s[12:13]
	s_bcnt1_i32_b64 s11, vcc
	s_add_i32 s11, s11, s10
	s_cmp_gt_u32 s11, 12
	s_cselect_b32 s0, s1, s0
	s_cselect_b32 s1, s14, s15
	v_cmp_le_u32_e64 s[12:13], s1, v32
	v_cmp_le_u32_e32 vcc, s1, v33
	s_or_b32 s14, s1, 0x40000
	s_or_b32 s15, s0, 0x40000
	s_bcnt1_i32_b64 s10, s[12:13]
	s_bcnt1_i32_b64 s11, vcc
	s_add_i32 s11, s11, s10
	s_cmp_gt_u32 s11, 12
	s_cselect_b32 s0, s1, s0
	s_cselect_b32 s1, s14, s15
	v_cmp_le_u32_e64 s[12:13], s1, v32
	v_cmp_le_u32_e32 vcc, s1, v33
	s_or_b32 s14, s1, 0x20000
	s_or_b32 s15, s0, 0x20000
	s_bcnt1_i32_b64 s10, s[12:13]
	s_bcnt1_i32_b64 s11, vcc
	s_add_i32 s11, s11, s10
	s_cmp_gt_u32 s11, 12
	s_cselect_b32 s0, s1, s0
	s_cselect_b32 s1, s14, s15
	v_cmp_le_u32_e64 s[12:13], s1, v32
	v_cmp_le_u32_e32 vcc, s1, v33
	s_or_b32 s14, s1, 0x10000
	s_or_b32 s15, s0, 0x10000
	s_bcnt1_i32_b64 s10, s[12:13]
	s_bcnt1_i32_b64 s11, vcc
	s_add_i32 s11, s11, s10
	s_cmp_gt_u32 s11, 12
	s_cselect_b32 s0, s1, s0
	s_cselect_b32 s1, s14, s15
	v_cmp_le_u32_e64 s[12:13], s1, v32
	v_cmp_le_u32_e32 vcc, s1, v33
	s_or_b32 s14, s1, 0x8000
	s_or_b32 s15, s0, 0x8000
	s_bcnt1_i32_b64 s10, s[12:13]
	s_bcnt1_i32_b64 s11, vcc
	s_add_i32 s11, s11, s10
	s_cmp_gt_u32 s11, 12
; DI void nsa_block(const bf16_t* P1, const bf16_t* VT1, const bf16_t* KSF, const bf16_t* KC, const bf16_t* VCT, bf16_t* O, const unsigned* kmx, int b, int g, int t0b, int wave, int lane, unsigned char* lds) {
;     ...
;                 const int cnt = __popcll(__ballot(ka >= trial)) + __popcll(__ballot(kb >= trial)); if (cnt >= 13) tau = trial; }
;             const unsigned long long eqA = __ballot(ka == tau), eqB = __ballot(kb == tau);
;             const int need = 13 - __popcll(__ballot(ka > tau)) - __popcll(__ballot(kb > tau));
;             const int rankA = __popcll(eqA & lt_mask), rankB = __popcll(eqA) + __popcll(eqB & lt_mask);
;             const bool selA = (ka > tau) || (ka == tau && rankA < need) || sa == 0 || sa == cur || sa == cur - 1;
;             const bool selB = (kb > tau) || (kb == tau && rankB < need) || sb == cur || sb == cur - 1;
;             ma = __ballot(selA); mb = __ballot(selB);
	s_cselect_b32 s0, s1, s0
	s_cselect_b32 s1, s14, s15
	v_cmp_le_u32_e64 s[12:13], s1, v32
	v_cmp_le_u32_e32 vcc, s1, v33
	s_or_b32 s14, s1, 0x4000
	s_or_b32 s15, s0, 0x4000
	s_bcnt1_i32_b64 s10, s[12:13]
	s_bcnt1_i32_b64 s11, vcc
	s_add_i32 s11, s11, s10
	s_cmp_gt_u32 s11, 12
	s_cselect_b32 s0, s1, s0
	s_cselect_b32 s1, s14, s15
	v_cmp_le_u32_e64 s[12:13], s1, v32
	v_cmp_le_u32_e32 vcc, s1, v33
	s_or_b32 s14, s1, 0x2000
	s_or_b32 s15, s0, 0x2000
	s_bcnt1_i32_b64 s10, s[12:13]
	s_bcnt1_i32_b64 s11, vcc
	s_add_i32 s11, s11, s10
	s_cmp_gt_u32 s11, 12
	s_cselect_b32 s0, s1, s0
	s_cselect_b32 s1, s14, s15
	v_cmp_le_u32_e64 s[12:13], s1, v32
	v_cmp_le_u32_e32 vcc, s1, v33
	s_or_b32 s14, s1, 0x1000
	s_or_b32 s15, s0, 0x1000
	s_bcnt1_i32_b64 s10, s[12:13]
	s_bcnt1_i32_b64 s11, vcc
	s_add_i32 s11, s11, s10
	s_cmp_gt_u32 s11, 12
	s_cselect_b32 s0, s1, s0
	s_cselect_b32 s1, s14, s15
	v_cmp_le_u32_e64 s[12:13], s1, v32
	v_cmp_le_u32_e32 vcc, s1, v33
	s_or_b32 s14, s1, 0x800
	s_or_b32 s15, s0, 0x800
	s_bcnt1_i32_b64 s10, s[12:13]
	s_bcnt1_i32_b64 s11, vcc
	s_add_i32 s11, s11, s10
	s_cmp_gt_u32 s11, 12
	s_cselect_b32 s0, s1, s0
	s_cselect_b32 s1, s14, s15
	v_cmp_le_u32_e64 s[12:13], s1, v32
	v_cmp_le_u32_e32 vcc, s1, v33
	s_or_b32 s14, s1, 0x400
	s_or_b32 s15, s0, 0x400
	s_bcnt1_i32_b64 s10, s[12:13]
	s_bcnt1_i32_b64 s11, vcc
	s_add_i32 s11, s11, s10
	s_cmp_gt_u32 s11, 12
	s_cselect_b32 s0, s1, s0
	s_cselect_b32 s1, s14, s15
	v_cmp_le_u32_e64 s[12:13], s1, v32
	v_cmp_le_u32_e32 vcc, s1, v33
	s_or_b32 s14, s1, 0x200
	s_or_b32 s15, s0, 0x200
	s_bcnt1_i32_b64 s10, s[12:13]
	s_bcnt1_i32_b64 s11, vcc
	s_add_i32 s11, s11, s10
	s_cmp_gt_u32 s11, 12
	s_cselect_b32 s0, s1, s0
	s_cselect_b32 s1, s14, s15
	v_cmp_le_u32_e64 s[12:13], s1, v32
	v_cmp_le_u32_e32 vcc, s1, v33
	s_or_b32 s14, s1, 0x100
	s_or_b32 s15, s0, 0x100
	s_bcnt1_i32_b64 s10, s[12:13]
	s_bcnt1_i32_b64 s11, vcc
	s_add_i32 s11, s11, s10
	s_cmp_gt_u32 s11, 12
	s_cselect_b32 s0, s1, s0
	s_cselect_b32 s1, s14, s15
	v_cmp_le_u32_e64 s[12:13], s1, v32
	v_cmp_le_u32_e32 vcc, s1, v33
	s_or_b32 s14, s1, 0x80
	s_or_b32 s15, s0, 0x80
	s_bcnt1_i32_b64 s10, s[12:13]
	s_bcnt1_i32_b64 s11, vcc
	s_add_i32 s11, s11, s10
	s_cmp_gt_u32 s11, 12
	s_cselect_b32 s0, s1, s0
	s_cselect_b32 s1, s14, s15
	v_cmp_le_u32_e64 s[12:13], s1, v32
	v_cmp_le_u32_e32 vcc, s1, v33
	s_or_b32 s14, s1, 64
	s_or_b32 s15, s0, 64
	s_bcnt1_i32_b64 s10, s[12:13]
	s_bcnt1_i32_b64 s11, vcc
	s_add_i32 s11, s11, s10
	s_cmp_gt_u32 s11, 12
	s_cselect_b32 s0, s1, s0
	s_cselect_b32 s1, s14, s15
	v_cmp_le_u32_e64 s[12:13], s1, v32
	v_cmp_le_u32_e32 vcc, s1, v33
	s_or_b32 s14, s1, 32
	s_or_b32 s15, s0, 32
	s_bcnt1_i32_b64 s10, s[12:13]
	s_bcnt1_i32_b64 s11, vcc
	s_add_i32 s11, s11, s10
	s_cmp_gt_u32 s11, 12
	s_cselect_b32 s0, s1, s0
	s_cselect_b32 s1, s14, s15
	v_cmp_le_u32_e64 s[12:13], s1, v32
	v_cmp_le_u32_e32 vcc, s1, v33
	s_or_b32 s14, s1, 16
	s_or_b32 s15, s0, 16
	s_bcnt1_i32_b64 s10, s[12:13]
	s_bcnt1_i32_b64 s11, vcc
	s_add_i32 s11, s11, s10
	s_cmp_gt_u32 s11, 12
	s_cselect_b32 s0, s1, s0
	s_cselect_b32 s1, s14, s15
	v_cmp_le_u32_e64 s[12:13], s1, v32
	v_cmp_le_u32_e32 vcc, s1, v33
	s_or_b32 s14, s1, 8
	s_or_b32 s15, s0, 8
	s_bcnt1_i32_b64 s10, s[12:13]
	s_bcnt1_i32_b64 s11, vcc
	s_add_i32 s11, s11, s10
	s_cmp_gt_u32 s11, 12
	s_cselect_b32 s0, s1, s0
	s_cselect_b32 s1, s14, s15
	v_cmp_le_u32_e64 s[12:13], s1, v32
	v_cmp_le_u32_e32 vcc, s1, v33
	s_or_b32 s14, s1, 4
	s_or_b32 s15, s0, 4
	s_bcnt1_i32_b64 s10, s[12:13]
	s_bcnt1_i32_b64 s11, vcc
	s_add_i32 s11, s11, s10
	s_cmp_gt_u32 s11, 12
	s_cselect_b32 s0, s1, s0
	s_cselect_b32 s1, s14, s15
	v_cmp_le_u32_e64 s[12:13], s1, v32
	v_cmp_le_u32_e32 vcc, s1, v33
	s_or_b32 s14, s1, 2
	s_or_b32 s15, s0, 2
	s_bcnt1_i32_b64 s10, s[12:13]
	s_bcnt1_i32_b64 s11, vcc
	s_add_i32 s11, s11, s10
	s_cmp_gt_u32 s11, 12
	s_cselect_b32 s0, s1, s0
	s_cselect_b32 s1, s14, s15
	v_cmp_le_u32_e64 s[12:13], s1, v32
	v_cmp_le_u32_e32 vcc, s1, v33
	s_or_b32 s14, s1, 1
	s_or_b32 s15, s0, 1
	s_bcnt1_i32_b64 s10, s[12:13]
	s_bcnt1_i32_b64 s11, vcc
	s_add_i32 s11, s11, s10
	s_cmp_gt_u32 s11, 12
	s_cselect_b32 s0, s1, s0
	s_cselect_b32 s1, s14, s15
	v_cmp_le_u32_e64 s[12:13], s1, v32
	v_cmp_le_u32_e32 vcc, s1, v33
	s_bcnt1_i32_b64 s10, s[12:13]
	s_bcnt1_i32_b64 s11, vcc
	s_add_i32 s11, s11, s10
	s_cmp_gt_u32 s11, 12
	s_cselect_b32 s16, s1, s0
	v_cmp_lt_u32_e32 vcc, s16, v32
	s_bcnt1_i32_b64 s17, vcc
	v_cmp_lt_u32_e32 vcc, s16, v33
	v_cmp_ne_u32_e64 s[12:13], s16, v32
	v_cmp_eq_u32_e64 s[10:11], s16, v32
	v_cmp_eq_u32_e64 s[0:1], s16, v33
	v_cmp_ge_u32_e64 s[14:15], s16, v32
	s_bcnt1_i32_b64 s16, vcc
	s_add_i32 s17, s17, s16
	s_sub_i32 s25, 13, s17
	s_and_saveexec_b64 s[16:17], s[14:15]
	s_cbranch_execz .LBB0_1026
	s_mov_b64 s[18:19], 0
	s_and_saveexec_b64 s[14:15], s[12:13]
	s_xor_b64 s[14:15], exec, s[14:15]
	s_cbranch_execz .LBB0_1031
	v_cmp_ne_u32_e64 s[12:13], v176, v38
	s_xor_b64 s[18:19], s[4:5], -1
	s_and_b64 s[12:13], s[18:19], s[12:13]
	s_and_b64 s[18:19], s[12:13], exec
	s_andn2_saveexec_b64 s[42:43], s[14:15]
	s_cbranch_execnz .LBB0_1032
